# SWA block: bias LUT widened to rel in [-192,192] (entries beyond +-128 hold -1e30) so the per-element clamp and address math disappear
# speedup vs baseline: 1.0353x; 1.0048x over previous
; #define LAS __attribute__((address_space(3)))
; DI void attn_lut(LAS float* LUT, int tid, const float* relb, int qhead) {
;     if (tid < 259) { const int rel = tid - 129, n = rel < 0 ? -rel : rel; int b;
;         if (n < 8) b = n; else { int m = (31 - __builtin_clz((unsigned)(n * n))) - 6; b = 8 + m; if (b > 15) b = 15; }
;         if (rel > 0) b += 16;
;         LUT[tid] = relb[b * 8 + qhead] * LOG2E; }
; template <int DQK, bool SWA>
; DI void attn_block(int wv, LAS unsigned char* lds, const bf16_t* Q, int ldq, int qoff, const bf16_t* K, int ldk, int koff, const bf16_t* Vt,
;                    int base, int T, int q0, bf16_t* O, int ldo, int ooff, const float* relb, int qhead, float sink_add) {
;     constexpr int KP = DQK * 2 + 16, CPR = DQK / 8, NKC = 64 * CPR, NKS = DQK / 16, KSZ = 13312;
;     const int tid = tid_(wv), lane = tid & 63, w = tid >> 6, r = lane & 31, h = lane >> 5;
;     LAS float* LUT = (LAS float*)(lds + ATT_LUT);
;     __syncthreads();
;     if (SWA) attn_lut(LUT, tid, relb, qhead);
;     const int qw0 = q0 + 32 * w, qpos = qw0 + r; const size_t qrow = (size_t)base + qpos;
;     bf16x8 qf[NKS];
; #pragma unroll
;     for (int ks = 0; ks < NKS; ++ks) qf[ks] = *(const bf16x8*)(Q + qrow * ldq + qoff + 16 * ks + 8 * h);
;     f32x16 o0, o1;
; #pragma unroll
;     for (int i = 0; i < 16; ++i) { o0[i] = 0.f; o1[i] = 0.f; }
;     float lsum = 0.f;
;     const int nt = (T + 63) >> 6;
;     int lo = 0, ntl = nt;
;     if (SWA) { lo = (q0 - 128) >> 6; if (lo < 1) lo = 1; int hi = (q0 + 255 + 128) >> 6; if (hi > nt - 1) hi = nt - 1; ntl = 1 + (hi >= lo ? hi - lo + 1 : 0); }
;     u32x4 kA0, kA1, vA, kB0, kB1, vB;
;     kA1 = (u32x4){0u, 0u, 0u, 0u}; kB1 = kA1;
;     const int kc0 = tid, kc1 = tid + 512;
.Lswaa_dec:
	s_lshr_b32 s15, s33, 6
	s_lshl_b32 s4, s10, 2
	s_sub_u32 s5, s4, 2
	s_cmp_eq_u32 s10, 0
	s_cselect_b32 s12, 1, s5
	s_add_u32 s5, s4, 5
	s_sub_u32 s6, s13, 1
	s_min_u32 s5, s5, s6
	s_sub_u32 s5, s5, s12
	s_add_u32 s29, s5, 1
	s_lshl_b32 s49, s10, 8
	s_lshl_b32 s4, s15, 5
	s_add_u32 s49, s49, s4
	s_movk_i32 s50, 0xff7f
	s_movk_i32 s51, 0xff80
	s_waitcnt lgkmcnt(0)
	s_lshl_b32 s4, s8, 2
	s_load_dword s46, s[44:45], s4
	v_add_u32_e32 v21, s33, v254
	v_add_u32_e32 v25, 0xffffff40, v21
	v_sub_u32_e32 v23, 0, v25
	v_max_i32_e32 v23, v25, v23
	v_mul_u32_u24_e32 v24, v23, v23
	v_ffbh_u32_e32 v24, v24
	v_sub_u32_e32 v24, 33, v24
	v_min_u32_e32 v24, 15, v24
	v_cmp_gt_u32_e32 vcc, 8, v23
	s_nop 1
	v_cndmask_b32_e32 v24, v24, v23, vcc
	v_cmp_lt_i32_e32 vcc, 0, v25
	s_nop 1
	v_cndmask_b32_e64 v23, 0, 16, vcc
	v_add_u32_e32 v24, v24, v23
	v_lshl_add_u32 v24, v24, 3, s8
	v_lshlrev_b32_e32 v24, 2, v24
	v_min_u32_e32 v24, 0x3fc, v24
	global_load_dword v24, v24, s[42:43]
	s_lshl_b32 s4, s8, 7
	s_add_u32 s16, s40, s4
	s_addc_u32 s17, s41, 0
	s_add_u32 s4, s4, 0x200
	s_add_u32 s22, s34, 0x19548000
	s_addc_u32 s23, s35, 0
	s_add_u32 s22, s22, s4
	s_addc_u32 s23, s23, 0
	s_lshr_b32 s5, s8, 2
	s_lshl_b32 s4, s5, 7
	s_lshl_b32 s6, s11, 8
	s_add_u32 s18, s40, 0x50c0000
	s_addc_u32 s19, s41, 0
	s_add_u32 s18, s18, s4
	s_addc_u32 s19, s19, 0
	s_add_u32 s18, s18, s6
	s_addc_u32 s19, s19, 0
	s_mul_i32 s4, s5, 0xa18000
	s_lshl_b32 s6, s11, 1
	s_add_u32 s20, s34, 0x300a8000
	s_addc_u32 s21, s35, 0
	s_add_u32 s20, s20, s4
	s_addc_u32 s21, s21, 0
	s_add_u32 s20, s20, s6
	s_addc_u32 s21, s21, 0
	v_and_b32_e32 v0, 31, v254
	v_lshrrev_b32_e32 v197, 5, v254
	v_mul_u32_u24_e32 v194, 0x90, v0
	v_add_u32_e32 v195, 0x2400, v194
	v_lshl_add_u32 v194, v197, 4, v194
	v_lshl_add_u32 v195, v197, 3, v195
	v_add_u32_e32 v196, 0x1200, v195
	v_add_u32_e32 v198, s49, v0
	v_lshlrev_b32_e32 v20, 2, v197
	v_sub_u32_e32 v20, v20, v198
	v_add_u32_e32 v198, s11, v198
	v_lshlrev_b32_e32 v199, 10, v198
	v_lshl_add_u32 v199, v197, 4, v199
	v_lshlrev_b32_e32 v198, 11, v198
	v_lshl_add_u32 v200, v197, 3, v198
	v_mov_b32_e32 v19, 0x81
	v_mov_b32_e32 v22, 0x80
	s_movk_i32 s48, 0x71c8
	s_mov_b32 s47, 0x28600
	s_movk_i32 s28, 0x80
	s_movk_i32 s27, 0x4000
	s_add_u32 s4, s15, 0
	s_cmpk_gt_u32 s4, 8
	s_cselect_b32 s7, s47, 0x100
	s_cselect_b32 s36, s28, s27
	s_mov_b32 s37, 0
	s_cselect_b32 s42, s20, s18
	s_cselect_b32 s43, s21, s19
	s_cselect_b32 s5, 9, 0
	s_cselect_b32 s6, 0x2400, 0
	s_sub_u32 s4, s4, s5
	s_cmpk_gt_u32 s4, 8
	s_cselect_b32 s5, 9, 0
	s_sub_u32 s4, s4, s5
	s_lshl_b32 s5, s4, 10
	s_add_u32 s24, s5, s6
	s_lshl_b32 s4, s4, 6
	v_add_u32_e32 v197, s4, v254
	v_mul_lo_u32 v198, v197, s48
	v_lshrrev_b32_e32 v198, 18, v198
	v_mul_u32_u24_e32 v186, 9, v198
	v_sub_u32_e32 v197, v197, v186
	v_cmp_ne_u32_e32 vcc, 8, v197
	s_nop 1
	v_cndmask_b32_e32 v197, 0, v197, vcc
	v_mul_lo_u32 v198, v198, s7
	v_lshl_add_u32 v186, v197, 4, v198
	v_mov_b32_e32 v187, 0
	v_lshl_add_u64 v[186:187], s[42:43], 0, v[186:187]
	s_add_u32 s4, s15, 8
	s_cmpk_gt_u32 s4, 8
	s_cselect_b32 s7, s47, 0x100
	s_cselect_b32 s38, s28, s27
	s_mov_b32 s39, 0
	s_cselect_b32 s42, s20, s18
	s_cselect_b32 s43, s21, s19
	s_cselect_b32 s5, 9, 0
	s_cselect_b32 s6, 0x2400, 0
	s_sub_u32 s4, s4, s5
	s_cmpk_gt_u32 s4, 8
	s_cselect_b32 s5, 9, 0
	s_sub_u32 s4, s4, s5
	s_lshl_b32 s5, s4, 10
	s_add_u32 s25, s5, s6
	s_lshl_b32 s4, s4, 6
	v_add_u32_e32 v197, s4, v254
	v_mul_lo_u32 v198, v197, s48
	v_lshrrev_b32_e32 v198, 18, v198
	v_mul_u32_u24_e32 v188, 9, v198
	v_sub_u32_e32 v197, v197, v188
	v_cmp_ne_u32_e32 vcc, 8, v197
	s_nop 1
	v_cndmask_b32_e32 v197, 0, v197, vcc
	v_mul_lo_u32 v198, v198, s7
	v_lshl_add_u32 v188, v197, 4, v198
	v_mov_b32_e32 v189, 0
	v_lshl_add_u64 v[188:189], s[42:43], 0, v[188:189]
	s_add_u32 s4, s15, 16
	s_cmpk_gt_u32 s4, 8
	s_cselect_b32 s7, s47, 0x100
	s_cselect_b32 s40, s28, s27
	s_mov_b32 s41, 0
; #define LAS __attribute__((address_space(3)))
; #define ATT_GLOAD(k0_, k1_, v_, tile) do { const size_t rb = (size_t)base + (size_t)(tile) * 64; \
;         k0_ = *(const u32x4*)(K + (rb + kkey0) * ldk + koff + kpart0 * 8); \
;         if (kc1 < NKC) k1_ = *(const u32x4*)(K + (rb + kkey1) * ldk + koff + kpart1 * 8); \
;         v_ = *(const u32x4*)(Vt + (size_t)vd * MPAD + rb + vpart * 8); } while (0)
; #define ATT_LWRITE(k0_, k1_, v_, b) do { LAS unsigned char* kb = lds + (b) * ATT_BUF; \
;         *(LAS u32x4*)(kb + kkey0 * KP + kpart0 * 16) = k0_; \
;         if (kc1 < NKC) *(LAS u32x4*)(kb + kkey1 * KP + kpart1 * 16) = k1_; \
;         *(LAS u32x4*)(kb + KSZ + vd * 144 + vpart * 16) = v_; } while (0)
; DI void attn_lut(LAS float* LUT, int tid, const float* relb, int qhead) {
;     if (tid < 259) { const int rel = tid - 129, n = rel < 0 ? -rel : rel; int b;
;         if (n < 8) b = n; else { int m = (31 - __builtin_clz((unsigned)(n * n))) - 6; b = 8 + m; if (b > 15) b = 15; }
;         if (rel > 0) b += 16;
;         LUT[tid] = relb[b * 8 + qhead] * LOG2E; }
; template <int DQK, bool SWA>
; DI void attn_block(int wv, LAS unsigned char* lds, const bf16_t* Q, int ldq, int qoff, const bf16_t* K, int ldk, int koff, const bf16_t* Vt,
;                    int base, int T, int q0, bf16_t* O, int ldo, int ooff, const float* relb, int qhead, float sink_add) {
;     ...
;     u32x4 kA0, kA1, vA, kB0, kB1, vB;
;     kA1 = (u32x4){0u, 0u, 0u, 0u}; kB1 = kA1;
;     const int kc0 = tid, kc1 = tid + 512;
;     const int kkey0 = kc0 / CPR, kpart0 = kc0 % CPR, kkey1 = kc1 / CPR, kpart1 = kc1 % CPR;
;     const int vd = tid >> 3, vpart = tid & 7;
;     ...
;     ATT_GLOAD(kA0, kA1, vA, ATT_TILE(0)); ATT_LWRITE(kA0, kA1, vA, 0);
;     if (ntl > 1) ATT_GLOAD(kB0, kB1, vB, ATT_TILE(1));
;     if (ntl > 2) ATT_GLOAD(kA0, kA1, vA, ATT_TILE(2));
;     __syncthreads();
	s_cselect_b32 s42, s20, s18
	s_cselect_b32 s43, s21, s19
	s_cselect_b32 s5, 9, 0
	s_cselect_b32 s6, 0x2400, 0
	s_sub_u32 s4, s4, s5
	s_cmpk_gt_u32 s4, 8
	s_cselect_b32 s5, 9, 0
	s_sub_u32 s4, s4, s5
	s_lshl_b32 s5, s4, 10
	s_add_u32 s26, s5, s6
	s_lshl_b32 s4, s4, 6
	v_add_u32_e32 v197, s4, v254
	v_mul_lo_u32 v198, v197, s48
	v_lshrrev_b32_e32 v198, 18, v198
	v_mul_u32_u24_e32 v190, 9, v198
	v_sub_u32_e32 v197, v197, v190
	v_cmp_ne_u32_e32 vcc, 8, v197
	s_nop 1
	v_cndmask_b32_e32 v197, 0, v197, vcc
	v_mul_lo_u32 v198, v198, s7
	v_lshl_add_u32 v190, v197, 4, v198
	v_mov_b32_e32 v191, 0
	v_lshl_add_u64 v[190:191], s[42:43], 0, v[190:191]
	global_load_dwordx4 v[2:5], v199, s[16:17] offset:0
	global_load_dwordx4 v[6:9], v199, s[16:17] offset:32
	global_load_dwordx4 v[10:13], v199, s[16:17] offset:64
	global_load_dwordx4 v[14:17], v199, s[16:17] offset:96
	s_mov_b32 s28, 0x0
	s_add_u32 m0, s28, s24
	s_nop 0
	global_load_lds_dwordx4 v[186:187], off
	s_mul_i32 s4, s36, s12
	s_mov_b32 s5, 0
	v_lshl_add_u64 v[186:187], v[186:187], 0, s[4:5]
	s_add_u32 m0, s28, s25
	s_nop 0
	global_load_lds_dwordx4 v[188:189], off
	s_mul_i32 s4, s38, s12
	s_mov_b32 s5, 0
	v_lshl_add_u64 v[188:189], v[188:189], 0, s[4:5]
	s_add_u32 m0, s28, s26
	s_nop 0
	global_load_lds_dwordx4 v[190:191], off
	s_mul_i32 s4, s40, s12
	s_mov_b32 s5, 0
	v_lshl_add_u64 v[190:191], v[190:191], 0, s[4:5]
	s_mov_b32 s28, 0x4800
	s_add_u32 m0, s28, s24
	s_nop 0
	global_load_lds_dwordx4 v[186:187], off
	v_lshl_add_u64 v[186:187], v[186:187], 0, s[36:37]
	s_add_u32 m0, s28, s25
	s_nop 0
	global_load_lds_dwordx4 v[188:189], off
	v_lshl_add_u64 v[188:189], v[188:189], 0, s[38:39]
	s_add_u32 m0, s28, s26
	s_nop 0
	global_load_lds_dwordx4 v[190:191], off
	v_lshl_add_u64 v[190:191], v[190:191], 0, s[40:41]
	s_mov_b32 s28, 0xf000
	s_add_u32 m0, s28, s24
	s_nop 0
	global_load_lds_dwordx4 v[186:187], off
	v_lshl_add_u64 v[186:187], v[186:187], 0, s[36:37]
	s_add_u32 m0, s28, s25
	s_nop 0
	global_load_lds_dwordx4 v[188:189], off
	v_lshl_add_u64 v[188:189], v[188:189], 0, s[38:39]
	s_add_u32 m0, s28, s26
	s_nop 0
	global_load_lds_dwordx4 v[190:191], off
	v_lshl_add_u64 v[190:191], v[190:191], 0, s[40:41]
	s_mov_b32 s28, 0x13800
	s_add_u32 m0, s28, s24
	s_nop 0
	global_load_lds_dwordx4 v[186:187], off
	v_lshl_add_u64 v[186:187], v[186:187], 0, s[36:37]
	s_add_u32 m0, s28, s25
	s_nop 0
	global_load_lds_dwordx4 v[188:189], off
	v_lshl_add_u64 v[188:189], v[188:189], 0, s[38:39]
	s_add_u32 m0, s28, s26
	s_nop 0
	global_load_lds_dwordx4 v[190:191], off
	v_lshl_add_u64 v[190:191], v[190:191], 0, s[40:41]
	v_mov_b32_e32 v26, 0
	v_mov_b32_e32 v27, 0
	v_mov_b32_e32 v28, 0
	v_mov_b32_e32 v29, 0
	v_mov_b32_e32 v30, 0
	v_mov_b32_e32 v31, 0
	v_mov_b32_e32 v32, 0
	v_mov_b32_e32 v33, 0
	v_mov_b32_e32 v34, 0
	v_mov_b32_e32 v35, 0
	v_mov_b32_e32 v36, 0
	v_mov_b32_e32 v37, 0
	v_mov_b32_e32 v38, 0
	v_mov_b32_e32 v39, 0
	v_mov_b32_e32 v40, 0
	v_mov_b32_e32 v41, 0
	v_mov_b32_e32 v42, 0
	v_mov_b32_e32 v43, 0
	v_mov_b32_e32 v44, 0
	v_mov_b32_e32 v45, 0
	v_mov_b32_e32 v46, 0
	v_mov_b32_e32 v47, 0
	v_mov_b32_e32 v48, 0
	v_mov_b32_e32 v49, 0
	v_mov_b32_e32 v50, 0
	v_mov_b32_e32 v51, 0
	v_mov_b32_e32 v52, 0
	v_mov_b32_e32 v53, 0
	v_mov_b32_e32 v54, 0
	v_mov_b32_e32 v55, 0
	v_mov_b32_e32 v56, 0
	v_mov_b32_e32 v57, 0
	v_mov_b32_e32 v192, 0
	v_mov_b32_e32 v193, 0
	s_waitcnt vmcnt(16)
	v_mul_f32_e32 v24, 0x3fb8aa3b, v24
	v_mov_b32_e32 v23, 0xf149f2ca
	v_add_u32_e32 v25, 0xffffff40, v21
	v_sub_u32_e32 v18, 0, v25
	v_max_i32_e32 v18, v25, v18
	v_cmp_lt_u32_e32 vcc, 0x80, v18
	s_nop 1
	v_cndmask_b32_e32 v24, v24, v23, vcc
	v_lshlrev_b32_e32 v25, 2, v21
	v_cmp_gt_u32_e32 vcc, 0x181, v21
	s_and_saveexec_b64 s[4:5], vcc
	ds_write_b32 v25, v24 offset:49152
	s_mov_b64 exec, s[4:5]
	s_mov_b32 s14, 0
	s_mov_b32 s30, 0x0
	s_mov_b32 s31, 0x18000
	s_waitcnt vmcnt(9) lgkmcnt(0)
	s_barrier
	s_cmpk_lt_u32 s15, 4
	s_cbranch_scc1 .Lswaa_noskew
	s_barrier

; DI unsigned pack2(float lo, float hi) { f32x2 v = {lo, hi}; bf16v2 r = __builtin_convertvector(v, bf16v2); return __builtin_bit_cast(unsigned, r); }
; DI float fexp2(float x) { return __builtin_amdgcn_exp2f(x); }
; #define MFMA32(a, b, c) __builtin_amdgcn_mfma_f32_32x32x16_bf16((a), (b), (c), 0, 0, 0)
; template <int DQK, bool SWA, bool MASK, class KF, class VF>
; DI void attn_subtile(const bf16x8 (&qf)[DQK / 16], f32x16& o0, f32x16& o1, float& lsum, int kbase, int h, int qpos, int T, const LAS float* LUT, KF kfrag, VF vfrag) {
;     ...
;     if (SWA) {
;         float bias[16];
; #pragma unroll
;         for (int i = 0; i < 16; ++i) {
;             const int rel = kbase + (i & 3) + 8 * (i >> 2) + 4 * h - qpos;
;             const int idx = rel < -129 ? -129 : (rel > 129 ? 129 : rel); bias[i] = LUT[idx + 129];
;         }
; #pragma unroll
;         for (int i = 0; i < 16; ++i) {
;             const int kpos = kbase + (i & 3) + 8 * (i >> 2) + 4 * h, rel = kpos - qpos;
;             const float e = fexp2(s[i] + bias[i]);
;             const bool vis = kpos < T && (kpos < 16 || (rel <= 128 && rel >= -128));
;             pv[i] = vis ? e : 0.f; lsum += pv[i];
;         }
;     } else {
; #pragma unroll
;         for (int i = 0; i < 16; ++i) {
;             const float e = fexp2(s[i]);
;             if (MASK) { const int kpos = kbase + (i & 3) + 8 * (i >> 2) + 4 * h; pv[i] = kpos < T ? e : 0.f; } else pv[i] = e;
;             lsum += pv[i];
;         }
;     }
; #pragma unroll
;     for (int s2 = 0; s2 < 2; ++s2) {
;         u32x4 pk = {pack2(pv[8 * s2], pv[8 * s2 + 1]), pack2(pv[8 * s2 + 2], pv[8 * s2 + 3]), pack2(pv[8 * s2 + 4], pv[8 * s2 + 5]), pack2(pv[8 * s2 + 6], pv[8 * s2 + 7])};
;         const bf16x8 pf = __builtin_bit_cast(bf16x8, pk);
;         o0 = MFMA32(s2 == 0 ? vf00 : vf01, pf, o0); o1 = MFMA32(s2 == 0 ? vf10 : vf11, pf, o1);
.Lswaa_xskip1:
	s_waitcnt vmcnt(6) lgkmcnt(0)
	s_barrier
	s_mov_b32 s28, s31
	s_add_u32 m0, s28, s24
	s_nop 0
	global_load_lds_dwordx4 v[186:187], off
	v_lshl_add_u64 v[186:187], v[186:187], 0, s[36:37]
	s_add_u32 m0, s28, s25
	s_nop 0
	global_load_lds_dwordx4 v[188:189], off
	v_lshl_add_u64 v[188:189], v[188:189], 0, s[38:39]
	s_add_u32 m0, s28, s26
	s_nop 0
	global_load_lds_dwordx4 v[190:191], off
	v_lshl_add_u64 v[190:191], v[190:191], 0, s[40:41]
	s_cmp_eq_u32 s42, 0
	s_cbranch_scc1 .Lswaa_y1
	s_cmp_eq_u32 s27, 0
	s_cbranch_scc1 .Lswaa_y0meta
	s_sub_u32 s5, s13, 1
	s_cmp_eq_u32 s27, s5
	s_cbranch_scc1 .Lswaa_y0last
	s_lshl_b32 s4, s27, 6
	v_add_u32_e32 v18, s4, v20
	v_lshlrev_b32_e32 v21, 2, v18
	ds_read_b32 v122, v21 offset:49920
	ds_read_b32 v123, v21 offset:49924
	ds_read_b32 v124, v21 offset:49928
	ds_read_b32 v125, v21 offset:49932
	ds_read_b32 v126, v21 offset:49952
	ds_read_b32 v127, v21 offset:49956
	ds_read_b32 v128, v21 offset:49960
	ds_read_b32 v129, v21 offset:49964
	ds_read_b32 v130, v21 offset:49984
	ds_read_b32 v131, v21 offset:49988
	ds_read_b32 v132, v21 offset:49992
	ds_read_b32 v133, v21 offset:49996
	ds_read_b32 v134, v21 offset:50016
	ds_read_b32 v135, v21 offset:50020
	ds_read_b32 v136, v21 offset:50024
	ds_read_b32 v137, v21 offset:50028
	s_waitcnt lgkmcnt(0)
	v_add_f32_e32 v58, v58, v122
	v_add_f32_e32 v59, v59, v123
	v_add_f32_e32 v60, v60, v124
	v_add_f32_e32 v61, v61, v125
	v_add_f32_e32 v62, v62, v126
	v_add_f32_e32 v63, v63, v127
	v_add_f32_e32 v64, v64, v128
	v_add_f32_e32 v65, v65, v129
	v_add_f32_e32 v66, v66, v130
	v_add_f32_e32 v67, v67, v131
	v_add_f32_e32 v68, v68, v132
	v_add_f32_e32 v69, v69, v133
	v_add_f32_e32 v70, v70, v134
	v_add_f32_e32 v71, v71, v135
	v_add_f32_e32 v72, v72, v136
	v_add_f32_e32 v73, v73, v137
	v_exp_f32_e32 v58, v58
	v_exp_f32_e32 v59, v59
	v_exp_f32_e32 v60, v60
	v_exp_f32_e32 v61, v61
	v_exp_f32_e32 v62, v62
	v_exp_f32_e32 v63, v63
	v_exp_f32_e32 v64, v64
	v_exp_f32_e32 v65, v65
	v_exp_f32_e32 v66, v66
	v_exp_f32_e32 v67, v67
	v_exp_f32_e32 v68, v68
	v_exp_f32_e32 v69, v69
	v_exp_f32_e32 v70, v70
	v_exp_f32_e32 v71, v71
	v_exp_f32_e32 v72, v72
	v_exp_f32_e32 v73, v73
	v_cvt_pk_bf16_f32 v170, v58, v59
	v_cvt_pk_bf16_f32 v171, v60, v61
	v_cvt_pk_bf16_f32 v172, v62, v63
	v_cvt_pk_bf16_f32 v173, v64, v65
	v_cvt_pk_bf16_f32 v174, v66, v67
	v_cvt_pk_bf16_f32 v175, v68, v69
	v_cvt_pk_bf16_f32 v176, v70, v71
	v_cvt_pk_bf16_f32 v177, v72, v73
	v_add_f32_e32 v192, v192, v58
	v_add_f32_e32 v193, v193, v59
	v_add_f32_e32 v192, v192, v60
	v_add_f32_e32 v193, v193, v61
	v_add_f32_e32 v192, v192, v62
	v_add_f32_e32 v193, v193, v63
	v_add_f32_e32 v192, v192, v64
	v_add_f32_e32 v193, v193, v65
	v_add_f32_e32 v192, v192, v66
	v_add_f32_e32 v193, v193, v67
	v_add_f32_e32 v192, v192, v68
	v_add_f32_e32 v193, v193, v69
	v_add_f32_e32 v192, v192, v70
	v_add_f32_e32 v193, v193, v71
	v_add_f32_e32 v192, v192, v72
	v_add_f32_e32 v193, v193, v73
	s_branch .Lswaa_y1
.Lswaa_y0meta:
	s_lshl_b32 s4, s27, 6
	v_add_u32_e32 v18, s4, v20
	v_med3_i32 v122, v18, s51, v22
	v_lshlrev_b32_e32 v122, 2, v122
	ds_read_b32 v122, v122 offset:49920
	v_add_u32_e32 v123, 1, v18
	v_med3_i32 v123, v123, s51, v22
	v_lshlrev_b32_e32 v123, 2, v123
	ds_read_b32 v123, v123 offset:49920
	v_add_u32_e32 v124, 2, v18
	v_med3_i32 v124, v124, s51, v22
	v_lshlrev_b32_e32 v124, 2, v124
	ds_read_b32 v124, v124 offset:49920
	v_add_u32_e32 v125, 3, v18
	v_med3_i32 v125, v125, s51, v22
	v_lshlrev_b32_e32 v125, 2, v125
	ds_read_b32 v125, v125 offset:49920
	v_add_u32_e32 v126, 8, v18
	v_med3_i32 v126, v126, s51, v22
	v_lshlrev_b32_e32 v126, 2, v126
	ds_read_b32 v126, v126 offset:49920
	v_add_u32_e32 v127, 9, v18
	v_med3_i32 v127, v127, s51, v22
	v_lshlrev_b32_e32 v127, 2, v127
	ds_read_b32 v127, v127 offset:49920
	v_add_u32_e32 v128, 10, v18
	v_med3_i32 v128, v128, s51, v22
	v_lshlrev_b32_e32 v128, 2, v128
	ds_read_b32 v128, v128 offset:49920
	v_add_u32_e32 v129, 11, v18
	v_med3_i32 v129, v129, s51, v22
	v_lshlrev_b32_e32 v129, 2, v129
	ds_read_b32 v129, v129 offset:49920
	v_add_u32_e32 v130, 16, v18
	v_med3_i32 v130, v130, s50, v19
	v_lshlrev_b32_e32 v130, 2, v130
	ds_read_b32 v130, v130 offset:49920
	v_add_u32_e32 v131, 17, v18
	v_med3_i32 v131, v131, s50, v19
	v_lshlrev_b32_e32 v131, 2, v131
	ds_read_b32 v131, v131 offset:49920
	v_add_u32_e32 v132, 18, v18
	v_med3_i32 v132, v132, s50, v19
	v_lshlrev_b32_e32 v132, 2, v132
	ds_read_b32 v132, v132 offset:49920
	v_add_u32_e32 v133, 19, v18
	v_med3_i32 v133, v133, s50, v19
	v_lshlrev_b32_e32 v133, 2, v133
	ds_read_b32 v133, v133 offset:49920
	v_add_u32_e32 v134, 24, v18
	v_med3_i32 v134, v134, s50, v19
	v_lshlrev_b32_e32 v134, 2, v134
	ds_read_b32 v134, v134 offset:49920
	v_add_u32_e32 v135, 25, v18
	v_med3_i32 v135, v135, s50, v19
	v_lshlrev_b32_e32 v135, 2, v135
	ds_read_b32 v135, v135 offset:49920
	v_add_u32_e32 v136, 26, v18
	v_med3_i32 v136, v136, s50, v19
	v_lshlrev_b32_e32 v136, 2, v136
	ds_read_b32 v136, v136 offset:49920
	v_add_u32_e32 v137, 27, v18
	v_med3_i32 v137, v137, s50, v19
	v_lshlrev_b32_e32 v137, 2, v137
	ds_read_b32 v137, v137 offset:49920
	s_waitcnt lgkmcnt(0)
	v_add_f32_e32 v58, v58, v122
	v_add_f32_e32 v59, v59, v123
	v_add_f32_e32 v60, v60, v124
	v_add_f32_e32 v61, v61, v125
	v_add_f32_e32 v62, v62, v126
	v_add_f32_e32 v63, v63, v127
	v_add_f32_e32 v64, v64, v128
	v_add_f32_e32 v65, v65, v129
	v_add_f32_e32 v66, v66, v130
	v_add_f32_e32 v67, v67, v131
	v_add_f32_e32 v68, v68, v132
	v_add_f32_e32 v69, v69, v133
	v_add_f32_e32 v70, v70, v134
	v_add_f32_e32 v71, v71, v135
	v_add_f32_e32 v72, v72, v136
	v_add_f32_e32 v73, v73, v137
	v_exp_f32_e32 v58, v58
	v_exp_f32_e32 v59, v59
	v_exp_f32_e32 v60, v60
	v_exp_f32_e32 v61, v61
	v_exp_f32_e32 v62, v62
	v_exp_f32_e32 v63, v63
	v_exp_f32_e32 v64, v64
	v_exp_f32_e32 v65, v65
	v_exp_f32_e32 v66, v66
	v_exp_f32_e32 v67, v67
	v_exp_f32_e32 v68, v68
	v_exp_f32_e32 v69, v69
	v_exp_f32_e32 v70, v70
	v_exp_f32_e32 v71, v71
	v_exp_f32_e32 v72, v72
	v_exp_f32_e32 v73, v73
	v_cvt_pk_bf16_f32 v170, v58, v59
	v_cvt_pk_bf16_f32 v171, v60, v61
	v_cvt_pk_bf16_f32 v172, v62, v63
	v_cvt_pk_bf16_f32 v173, v64, v65
	v_cvt_pk_bf16_f32 v174, v66, v67
	v_cvt_pk_bf16_f32 v175, v68, v69
	v_cvt_pk_bf16_f32 v176, v70, v71
	v_cvt_pk_bf16_f32 v177, v72, v73
	v_add_f32_e32 v192, v192, v58
	v_add_f32_e32 v193, v193, v59
	v_add_f32_e32 v192, v192, v60
	v_add_f32_e32 v193, v193, v61
	v_add_f32_e32 v192, v192, v62
	v_add_f32_e32 v193, v193, v63
	v_add_f32_e32 v192, v192, v64
	v_add_f32_e32 v193, v193, v65
	v_add_f32_e32 v192, v192, v66
	v_add_f32_e32 v193, v193, v67
	v_add_f32_e32 v192, v192, v68
	v_add_f32_e32 v193, v193, v69
	v_add_f32_e32 v192, v192, v70
	v_add_f32_e32 v193, v193, v71
	v_add_f32_e32 v192, v192, v72
	v_add_f32_e32 v193, v193, v73
	s_branch .Lswaa_y1
; DI unsigned pack2(float lo, float hi) { f32x2 v = {lo, hi}; bf16v2 r = __builtin_convertvector(v, bf16v2); return __builtin_bit_cast(unsigned, r); }
; DI float fexp2(float x) { return __builtin_amdgcn_exp2f(x); }
; #define MFMA32(a, b, c) __builtin_amdgcn_mfma_f32_32x32x16_bf16((a), (b), (c), 0, 0, 0)
; template <int DQK, bool SWA, bool MASK, class KF, class VF>
; DI void attn_subtile(const bf16x8 (&qf)[DQK / 16], f32x16& o0, f32x16& o1, float& lsum, int kbase, int h, int qpos, int T, const LAS float* LUT, KF kfrag, VF vfrag) {
;     ...
;     if (SWA) {
;         float bias[16];
; #pragma unroll
;         for (int i = 0; i < 16; ++i) {
;             const int rel = kbase + (i & 3) + 8 * (i >> 2) + 4 * h - qpos;
;             const int idx = rel < -129 ? -129 : (rel > 129 ? 129 : rel); bias[i] = LUT[idx + 129];
;         }
; #pragma unroll
;         for (int i = 0; i < 16; ++i) {
;             const int kpos = kbase + (i & 3) + 8 * (i >> 2) + 4 * h, rel = kpos - qpos;
;             const float e = fexp2(s[i] + bias[i]);
;             const bool vis = kpos < T && (kpos < 16 || (rel <= 128 && rel >= -128));
;             pv[i] = vis ? e : 0.f; lsum += pv[i];
;         }
;     } else {
; #pragma unroll
;         for (int i = 0; i < 16; ++i) {
;             const float e = fexp2(s[i]);
;             if (MASK) { const int kpos = kbase + (i & 3) + 8 * (i >> 2) + 4 * h; pv[i] = kpos < T ? e : 0.f; } else pv[i] = e;
;             lsum += pv[i];
;         }
;     }
; #pragma unroll
;     for (int s2 = 0; s2 < 2; ++s2) {
;         u32x4 pk = {pack2(pv[8 * s2], pv[8 * s2 + 1]), pack2(pv[8 * s2 + 2], pv[8 * s2 + 3]), pack2(pv[8 * s2 + 4], pv[8 * s2 + 5]), pack2(pv[8 * s2 + 6], pv[8 * s2 + 7])};
;         const bf16x8 pf = __builtin_bit_cast(bf16x8, pk);
;         o0 = MFMA32(s2 == 0 ? vf00 : vf01, pf, o0); o1 = MFMA32(s2 == 0 ? vf10 : vf11, pf, o1);
.Lswaa_y0last:
	s_lshl_b32 s4, s27, 6
	v_add_u32_e32 v18, s4, v20
	v_lshlrev_b32_e32 v21, 2, v18
	ds_read_b32 v122, v21 offset:49920
	ds_read_b32 v123, v21 offset:49924
	ds_read_b32 v124, v21 offset:49928
	ds_read_b32 v125, v21 offset:49932
	ds_read_b32 v126, v21 offset:49952
	ds_read_b32 v127, v21 offset:49956
	ds_read_b32 v128, v21 offset:49960
	ds_read_b32 v129, v21 offset:49964
	s_waitcnt lgkmcnt(0)
	v_add_f32_e32 v58, v58, v122
	v_add_f32_e32 v59, v59, v123
	v_add_f32_e32 v60, v60, v124
	v_add_f32_e32 v61, v61, v125
	v_add_f32_e32 v62, v62, v126
	v_add_f32_e32 v63, v63, v127
	v_add_f32_e32 v64, v64, v128
	v_add_f32_e32 v65, v65, v129
	v_mov_b32_e32 v66, 0
	v_mov_b32_e32 v67, 0
	v_mov_b32_e32 v68, 0
	v_mov_b32_e32 v69, 0
	v_mov_b32_e32 v70, 0
	v_mov_b32_e32 v71, 0
	v_mov_b32_e32 v72, 0
	v_mov_b32_e32 v73, 0
	v_exp_f32_e32 v58, v58
	v_exp_f32_e32 v59, v59
	v_exp_f32_e32 v60, v60
	v_exp_f32_e32 v61, v61
	v_exp_f32_e32 v62, v62
	v_exp_f32_e32 v63, v63
	v_exp_f32_e32 v64, v64
	v_exp_f32_e32 v65, v65
	v_cvt_pk_bf16_f32 v170, v58, v59
	v_cvt_pk_bf16_f32 v171, v60, v61
	v_cvt_pk_bf16_f32 v172, v62, v63
	v_cvt_pk_bf16_f32 v173, v64, v65
	v_cvt_pk_bf16_f32 v174, v66, v67
	v_cvt_pk_bf16_f32 v175, v68, v69
	v_cvt_pk_bf16_f32 v176, v70, v71
	v_cvt_pk_bf16_f32 v177, v72, v73
	v_add_f32_e32 v192, v192, v58
	v_add_f32_e32 v193, v193, v59
	v_add_f32_e32 v192, v192, v60
	v_add_f32_e32 v193, v193, v61
	v_add_f32_e32 v192, v192, v62
	v_add_f32_e32 v193, v193, v63
	v_add_f32_e32 v192, v192, v64
	v_add_f32_e32 v193, v193, v65
	v_add_f32_e32 v192, v192, v66
	v_add_f32_e32 v193, v193, v67
	v_add_f32_e32 v192, v192, v68
	v_add_f32_e32 v193, v193, v69
	v_add_f32_e32 v192, v192, v70
	v_add_f32_e32 v193, v193, v71
	v_add_f32_e32 v192, v192, v72
	v_add_f32_e32 v193, v193, v73
.Lswaa_y1:
	s_cmp_eq_u32 s43, 0
	s_cbranch_scc1 .Lswaa_ypv
	s_lshl_b32 s4, s27, 6
	s_add_u32 s4, s4, 32
	v_add_u32_e32 v18, s4, v20
	v_lshlrev_b32_e32 v21, 2, v18
	ds_read_b32 v122, v21 offset:49920
	ds_read_b32 v123, v21 offset:49924
	ds_read_b32 v124, v21 offset:49928
	ds_read_b32 v125, v21 offset:49932
	ds_read_b32 v126, v21 offset:49952
	ds_read_b32 v127, v21 offset:49956
	ds_read_b32 v128, v21 offset:49960
	ds_read_b32 v129, v21 offset:49964
	ds_read_b32 v130, v21 offset:49984
	ds_read_b32 v131, v21 offset:49988
	ds_read_b32 v132, v21 offset:49992
	ds_read_b32 v133, v21 offset:49996
	ds_read_b32 v134, v21 offset:50016
	ds_read_b32 v135, v21 offset:50020
	ds_read_b32 v136, v21 offset:50024
	ds_read_b32 v137, v21 offset:50028
	s_waitcnt lgkmcnt(0)
	v_add_f32_e32 v74, v74, v122
	v_add_f32_e32 v75, v75, v123
	v_add_f32_e32 v76, v76, v124
	v_add_f32_e32 v77, v77, v125
	v_add_f32_e32 v78, v78, v126
	v_add_f32_e32 v79, v79, v127
	v_add_f32_e32 v80, v80, v128
	v_add_f32_e32 v81, v81, v129
	v_add_f32_e32 v82, v82, v130
	v_add_f32_e32 v83, v83, v131
	v_add_f32_e32 v84, v84, v132
	v_add_f32_e32 v85, v85, v133
	v_add_f32_e32 v86, v86, v134
	v_add_f32_e32 v87, v87, v135
	v_add_f32_e32 v88, v88, v136
	v_add_f32_e32 v89, v89, v137
	v_exp_f32_e32 v74, v74
	v_exp_f32_e32 v75, v75
	v_exp_f32_e32 v76, v76
	v_exp_f32_e32 v77, v77
	v_exp_f32_e32 v78, v78
	v_exp_f32_e32 v79, v79
	v_exp_f32_e32 v80, v80
	v_exp_f32_e32 v81, v81
	v_exp_f32_e32 v82, v82
	v_exp_f32_e32 v83, v83
	v_exp_f32_e32 v84, v84
	v_exp_f32_e32 v85, v85
	v_exp_f32_e32 v86, v86
	v_exp_f32_e32 v87, v87
	v_exp_f32_e32 v88, v88
	v_exp_f32_e32 v89, v89
	v_cvt_pk_bf16_f32 v178, v74, v75
	v_cvt_pk_bf16_f32 v179, v76, v77
	v_cvt_pk_bf16_f32 v180, v78, v79
	v_cvt_pk_bf16_f32 v181, v80, v81
	v_cvt_pk_bf16_f32 v182, v82, v83
	v_cvt_pk_bf16_f32 v183, v84, v85
	v_cvt_pk_bf16_f32 v184, v86, v87
	v_cvt_pk_bf16_f32 v185, v88, v89
	v_add_f32_e32 v192, v192, v74
	v_add_f32_e32 v193, v193, v75
	v_add_f32_e32 v192, v192, v76
	v_add_f32_e32 v193, v193, v77
	v_add_f32_e32 v192, v192, v78
	v_add_f32_e32 v193, v193, v79
	v_add_f32_e32 v192, v192, v80
	v_add_f32_e32 v193, v193, v81
	v_add_f32_e32 v192, v192, v82
	v_add_f32_e32 v193, v193, v83
	v_add_f32_e32 v192, v192, v84
	v_add_f32_e32 v193, v193, v85
	v_add_f32_e32 v192, v192, v86
	v_add_f32_e32 v193, v193, v87
	v_add_f32_e32 v192, v192, v88
	v_add_f32_e32 v193, v193, v89

; #define LAS __attribute__((address_space(3)))
; DI void attn_lut(LAS float* LUT, int tid, const float* relb, int qhead) {
;     if (tid < 259) { const int rel = tid - 129, n = rel < 0 ? -rel : rel; int b;
;         if (n < 8) b = n; else { int m = (31 - __builtin_clz((unsigned)(n * n))) - 6; b = 8 + m; if (b > 15) b = 15; }
;         if (rel > 0) b += 16;
;         LUT[tid] = relb[b * 8 + qhead] * LOG2E; }
; template <int DQK, bool SWA>
; DI void attn_block(int wv, LAS unsigned char* lds, const bf16_t* Q, int ldq, int qoff, const bf16_t* K, int ldk, int koff, const bf16_t* Vt,
;                    int base, int T, int q0, bf16_t* O, int ldo, int ooff, const float* relb, int qhead, float sink_add) {
;     constexpr int KP = DQK * 2 + 16, CPR = DQK / 8, NKC = 64 * CPR, NKS = DQK / 16, KSZ = 13312;
;     const int tid = tid_(wv), lane = tid & 63, w = tid >> 6, r = lane & 31, h = lane >> 5;
;     LAS float* LUT = (LAS float*)(lds + ATT_LUT);
;     __syncthreads();
;     if (SWA) attn_lut(LUT, tid, relb, qhead);
;     const int qw0 = q0 + 32 * w, qpos = qw0 + r; const size_t qrow = (size_t)base + qpos;
;     bf16x8 qf[NKS];
; #pragma unroll
;     for (int ks = 0; ks < NKS; ++ks) qf[ks] = *(const bf16x8*)(Q + qrow * ldq + qoff + 16 * ks + 8 * h);
;     f32x16 o0, o1;
; #pragma unroll
;     for (int i = 0; i < 16; ++i) { o0[i] = 0.f; o1[i] = 0.f; }
;     float lsum = 0.f;
;     const int nt = (T + 63) >> 6;
;     int lo = 0, ntl = nt;
;     if (SWA) { lo = (q0 - 128) >> 6; if (lo < 1) lo = 1; int hi = (q0 + 255 + 128) >> 6; if (hi > nt - 1) hi = nt - 1; ntl = 1 + (hi >= lo ? hi - lo + 1 : 0); }
;     u32x4 kA0, kA1, vA, kB0, kB1, vB;
;     kA1 = (u32x4){0u, 0u, 0u, 0u}; kB1 = kA1;
;     const int kc0 = tid, kc1 = tid + 512;
.Lswab_dec:
	s_lshr_b32 s15, s33, 6
	s_lshl_b32 s4, s10, 2
	s_sub_u32 s5, s4, 2
	s_cmp_eq_u32 s10, 0
	s_cselect_b32 s12, 1, s5
	s_add_u32 s5, s4, 5
	s_sub_u32 s6, s13, 1
	s_min_u32 s5, s5, s6
	s_sub_u32 s5, s5, s12
	s_add_u32 s29, s5, 1
	s_lshl_b32 s49, s10, 8
	s_lshl_b32 s4, s15, 5
	s_add_u32 s49, s49, s4
	s_movk_i32 s50, 0xff7f
	s_movk_i32 s51, 0xff80
	s_waitcnt lgkmcnt(0)
	s_lshl_b32 s4, s8, 2
	s_add_u32 s4, s4, 32
	s_load_dword s46, s[44:45], s4
	v_add_u32_e32 v21, s33, v254
	v_add_u32_e32 v25, 0xffffff40, v21
	v_sub_u32_e32 v23, 0, v25
	v_max_i32_e32 v23, v25, v23
	v_mul_u32_u24_e32 v24, v23, v23
	v_ffbh_u32_e32 v24, v24
	v_sub_u32_e32 v24, 33, v24
	v_min_u32_e32 v24, 15, v24
	v_cmp_gt_u32_e32 vcc, 8, v23
	s_nop 1
	v_cndmask_b32_e32 v24, v24, v23, vcc
	v_cmp_lt_i32_e32 vcc, 0, v25
	s_nop 1
	v_cndmask_b32_e64 v23, 0, 16, vcc
	v_add_u32_e32 v24, v24, v23
	v_lshl_add_u32 v24, v24, 3, s8
	v_lshlrev_b32_e32 v24, 2, v24
	v_min_u32_e32 v24, 0x3fc, v24
	global_load_dword v24, v24, s[42:43]
	s_lshl_b32 s4, s8, 7
	s_add_u32 s16, s40, s4
	s_addc_u32 s17, s41, 0
	s_add_u32 s4, s4, 0x200
	s_add_u32 s22, s34, 0x19548000
	s_addc_u32 s23, s35, 0
	s_add_u32 s22, s22, s4
	s_addc_u32 s23, s23, 0
	s_lshr_b32 s5, s8, 2
	s_lshl_b32 s4, s5, 7
	s_lshl_b32 s6, s11, 8
	s_add_u32 s18, s40, 0x50c0000
	s_addc_u32 s19, s41, 0
	s_add_u32 s18, s18, s4
	s_addc_u32 s19, s19, 0
	s_add_u32 s18, s18, s6
	s_addc_u32 s19, s19, 0
	s_mul_i32 s4, s5, 0xa18000
	s_lshl_b32 s6, s11, 1
	s_add_u32 s20, s34, 0x300a8000
	s_addc_u32 s21, s35, 0
	s_add_u32 s20, s20, s4
	s_addc_u32 s21, s21, 0
	s_add_u32 s20, s20, s6
	s_addc_u32 s21, s21, 0
	v_and_b32_e32 v0, 31, v254
	v_lshrrev_b32_e32 v197, 5, v254
	v_mul_u32_u24_e32 v194, 0x90, v0
	v_add_u32_e32 v195, 0x2400, v194
	v_lshl_add_u32 v194, v197, 4, v194
	v_lshl_add_u32 v195, v197, 3, v195
	v_add_u32_e32 v196, 0x1200, v195
	v_add_u32_e32 v198, s49, v0
	v_lshlrev_b32_e32 v20, 2, v197
	v_sub_u32_e32 v20, v20, v198
	v_add_u32_e32 v198, s11, v198
	v_lshlrev_b32_e32 v199, 10, v198
	v_lshl_add_u32 v199, v197, 4, v199
	v_lshlrev_b32_e32 v198, 11, v198
	v_lshl_add_u32 v200, v197, 3, v198
	v_mov_b32_e32 v19, 0x81
	v_mov_b32_e32 v22, 0x80
	s_movk_i32 s48, 0x71c8
	s_mov_b32 s47, 0x28600
	s_movk_i32 s28, 0x80
	s_movk_i32 s27, 0x4000
	s_add_u32 s4, s15, 0
	s_cmpk_gt_u32 s4, 8
	s_cselect_b32 s7, s47, 0x100
	s_cselect_b32 s36, s28, s27
	s_mov_b32 s37, 0
	s_cselect_b32 s42, s20, s18
	s_cselect_b32 s43, s21, s19
	s_cselect_b32 s5, 9, 0
	s_cselect_b32 s6, 0x2400, 0
	s_sub_u32 s4, s4, s5
	s_cmpk_gt_u32 s4, 8
	s_cselect_b32 s5, 9, 0
	s_sub_u32 s4, s4, s5
	s_lshl_b32 s5, s4, 10
	s_add_u32 s24, s5, s6
	s_lshl_b32 s4, s4, 6
	v_add_u32_e32 v197, s4, v254
	v_mul_lo_u32 v198, v197, s48
	v_lshrrev_b32_e32 v198, 18, v198
	v_mul_u32_u24_e32 v186, 9, v198
	v_sub_u32_e32 v197, v197, v186
	v_cmp_ne_u32_e32 vcc, 8, v197
	s_nop 1
	v_cndmask_b32_e32 v197, 0, v197, vcc
	v_mul_lo_u32 v198, v198, s7
	v_lshl_add_u32 v186, v197, 4, v198
	v_mov_b32_e32 v187, 0
	v_lshl_add_u64 v[186:187], s[42:43], 0, v[186:187]
	s_add_u32 s4, s15, 8
	s_cmpk_gt_u32 s4, 8
	s_cselect_b32 s7, s47, 0x100
	s_cselect_b32 s38, s28, s27
	s_mov_b32 s39, 0
	s_cselect_b32 s42, s20, s18
	s_cselect_b32 s43, s21, s19
	s_cselect_b32 s5, 9, 0
	s_cselect_b32 s6, 0x2400, 0
	s_sub_u32 s4, s4, s5
	s_cmpk_gt_u32 s4, 8
	s_cselect_b32 s5, 9, 0
	s_sub_u32 s4, s4, s5
	s_lshl_b32 s5, s4, 10
	s_add_u32 s25, s5, s6
	s_lshl_b32 s4, s4, 6
	v_add_u32_e32 v197, s4, v254
	v_mul_lo_u32 v198, v197, s48
	v_lshrrev_b32_e32 v198, 18, v198
	v_mul_u32_u24_e32 v188, 9, v198
	v_sub_u32_e32 v197, v197, v188
	v_cmp_ne_u32_e32 vcc, 8, v197
	s_nop 1
	v_cndmask_b32_e32 v197, 0, v197, vcc
	v_mul_lo_u32 v198, v198, s7
	v_lshl_add_u32 v188, v197, 4, v198
	v_mov_b32_e32 v189, 0
	v_lshl_add_u64 v[188:189], s[42:43], 0, v[188:189]
	s_add_u32 s4, s15, 16
	s_cmpk_gt_u32 s4, 8
	s_cselect_b32 s7, s47, 0x100
	s_cselect_b32 s40, s28, s27
	s_mov_b32 s41, 0
; #define LAS __attribute__((address_space(3)))
; #define ATT_GLOAD(k0_, k1_, v_, tile) do { const size_t rb = (size_t)base + (size_t)(tile) * 64; \
;         k0_ = *(const u32x4*)(K + (rb + kkey0) * ldk + koff + kpart0 * 8); \
;         if (kc1 < NKC) k1_ = *(const u32x4*)(K + (rb + kkey1) * ldk + koff + kpart1 * 8); \
;         v_ = *(const u32x4*)(Vt + (size_t)vd * MPAD + rb + vpart * 8); } while (0)
; #define ATT_LWRITE(k0_, k1_, v_, b) do { LAS unsigned char* kb = lds + (b) * ATT_BUF; \
;         *(LAS u32x4*)(kb + kkey0 * KP + kpart0 * 16) = k0_; \
;         if (kc1 < NKC) *(LAS u32x4*)(kb + kkey1 * KP + kpart1 * 16) = k1_; \
;         *(LAS u32x4*)(kb + KSZ + vd * 144 + vpart * 16) = v_; } while (0)
; DI void attn_lut(LAS float* LUT, int tid, const float* relb, int qhead) {
;     if (tid < 259) { const int rel = tid - 129, n = rel < 0 ? -rel : rel; int b;
;         if (n < 8) b = n; else { int m = (31 - __builtin_clz((unsigned)(n * n))) - 6; b = 8 + m; if (b > 15) b = 15; }
;         if (rel > 0) b += 16;
;         LUT[tid] = relb[b * 8 + qhead] * LOG2E; }
; template <int DQK, bool SWA>
; DI void attn_block(int wv, LAS unsigned char* lds, const bf16_t* Q, int ldq, int qoff, const bf16_t* K, int ldk, int koff, const bf16_t* Vt,
;                    int base, int T, int q0, bf16_t* O, int ldo, int ooff, const float* relb, int qhead, float sink_add) {
;     ...
;     u32x4 kA0, kA1, vA, kB0, kB1, vB;
;     kA1 = (u32x4){0u, 0u, 0u, 0u}; kB1 = kA1;
;     const int kc0 = tid, kc1 = tid + 512;
;     const int kkey0 = kc0 / CPR, kpart0 = kc0 % CPR, kkey1 = kc1 / CPR, kpart1 = kc1 % CPR;
;     const int vd = tid >> 3, vpart = tid & 7;
;     ...
;     ATT_GLOAD(kA0, kA1, vA, ATT_TILE(0)); ATT_LWRITE(kA0, kA1, vA, 0);
;     if (ntl > 1) ATT_GLOAD(kB0, kB1, vB, ATT_TILE(1));
;     if (ntl > 2) ATT_GLOAD(kA0, kA1, vA, ATT_TILE(2));
;     __syncthreads();
	s_cselect_b32 s42, s20, s18
	s_cselect_b32 s43, s21, s19
	s_cselect_b32 s5, 9, 0
	s_cselect_b32 s6, 0x2400, 0
	s_sub_u32 s4, s4, s5
	s_cmpk_gt_u32 s4, 8
	s_cselect_b32 s5, 9, 0
	s_sub_u32 s4, s4, s5
	s_lshl_b32 s5, s4, 10
	s_add_u32 s26, s5, s6
	s_lshl_b32 s4, s4, 6
	v_add_u32_e32 v197, s4, v254
	v_mul_lo_u32 v198, v197, s48
	v_lshrrev_b32_e32 v198, 18, v198
	v_mul_u32_u24_e32 v190, 9, v198
	v_sub_u32_e32 v197, v197, v190
	v_cmp_ne_u32_e32 vcc, 8, v197
	s_nop 1
	v_cndmask_b32_e32 v197, 0, v197, vcc
	v_mul_lo_u32 v198, v198, s7
	v_lshl_add_u32 v190, v197, 4, v198
	v_mov_b32_e32 v191, 0
	v_lshl_add_u64 v[190:191], s[42:43], 0, v[190:191]
	global_load_dwordx4 v[2:5], v199, s[16:17] offset:0
	global_load_dwordx4 v[6:9], v199, s[16:17] offset:32
	global_load_dwordx4 v[10:13], v199, s[16:17] offset:64
	global_load_dwordx4 v[14:17], v199, s[16:17] offset:96
	s_mov_b32 s28, 0x0
	s_add_u32 m0, s28, s24
	s_nop 0
	global_load_lds_dwordx4 v[186:187], off
	s_mul_i32 s4, s36, s12
	s_mov_b32 s5, 0
	v_lshl_add_u64 v[186:187], v[186:187], 0, s[4:5]
	s_add_u32 m0, s28, s25
	s_nop 0
	global_load_lds_dwordx4 v[188:189], off
	s_mul_i32 s4, s38, s12
	s_mov_b32 s5, 0
	v_lshl_add_u64 v[188:189], v[188:189], 0, s[4:5]
	s_add_u32 m0, s28, s26
	s_nop 0
	global_load_lds_dwordx4 v[190:191], off
	s_mul_i32 s4, s40, s12
	s_mov_b32 s5, 0
	v_lshl_add_u64 v[190:191], v[190:191], 0, s[4:5]
	s_mov_b32 s28, 0x4800
	s_add_u32 m0, s28, s24
	s_nop 0
	global_load_lds_dwordx4 v[186:187], off
	v_lshl_add_u64 v[186:187], v[186:187], 0, s[36:37]
	s_add_u32 m0, s28, s25
	s_nop 0
	global_load_lds_dwordx4 v[188:189], off
	v_lshl_add_u64 v[188:189], v[188:189], 0, s[38:39]
	s_add_u32 m0, s28, s26
	s_nop 0
	global_load_lds_dwordx4 v[190:191], off
	v_lshl_add_u64 v[190:191], v[190:191], 0, s[40:41]
	s_mov_b32 s28, 0xf000
	s_add_u32 m0, s28, s24
	s_nop 0
	global_load_lds_dwordx4 v[186:187], off
	v_lshl_add_u64 v[186:187], v[186:187], 0, s[36:37]
	s_add_u32 m0, s28, s25
	s_nop 0
	global_load_lds_dwordx4 v[188:189], off
	v_lshl_add_u64 v[188:189], v[188:189], 0, s[38:39]
	s_add_u32 m0, s28, s26
	s_nop 0
	global_load_lds_dwordx4 v[190:191], off
	v_lshl_add_u64 v[190:191], v[190:191], 0, s[40:41]
	s_mov_b32 s28, 0x13800
	s_add_u32 m0, s28, s24
	s_nop 0
	global_load_lds_dwordx4 v[186:187], off
	v_lshl_add_u64 v[186:187], v[186:187], 0, s[36:37]
	s_add_u32 m0, s28, s25
	s_nop 0
	global_load_lds_dwordx4 v[188:189], off
	v_lshl_add_u64 v[188:189], v[188:189], 0, s[38:39]
	s_add_u32 m0, s28, s26
	s_nop 0
	global_load_lds_dwordx4 v[190:191], off
	v_lshl_add_u64 v[190:191], v[190:191], 0, s[40:41]
	v_mov_b32_e32 v26, 0
	v_mov_b32_e32 v27, 0
	v_mov_b32_e32 v28, 0
	v_mov_b32_e32 v29, 0
	v_mov_b32_e32 v30, 0
	v_mov_b32_e32 v31, 0
	v_mov_b32_e32 v32, 0
	v_mov_b32_e32 v33, 0
	v_mov_b32_e32 v34, 0
	v_mov_b32_e32 v35, 0
	v_mov_b32_e32 v36, 0
	v_mov_b32_e32 v37, 0
	v_mov_b32_e32 v38, 0
	v_mov_b32_e32 v39, 0
	v_mov_b32_e32 v40, 0
	v_mov_b32_e32 v41, 0
	v_mov_b32_e32 v42, 0
	v_mov_b32_e32 v43, 0
	v_mov_b32_e32 v44, 0
	v_mov_b32_e32 v45, 0
	v_mov_b32_e32 v46, 0
	v_mov_b32_e32 v47, 0
	v_mov_b32_e32 v48, 0
	v_mov_b32_e32 v49, 0
	v_mov_b32_e32 v50, 0
	v_mov_b32_e32 v51, 0
	v_mov_b32_e32 v52, 0
	v_mov_b32_e32 v53, 0
	v_mov_b32_e32 v54, 0
	v_mov_b32_e32 v55, 0
	v_mov_b32_e32 v56, 0
	v_mov_b32_e32 v57, 0
	v_mov_b32_e32 v192, 0
	v_mov_b32_e32 v193, 0
	s_waitcnt vmcnt(16)
	v_mul_f32_e32 v24, 0x3fb8aa3b, v24
	v_mov_b32_e32 v23, 0xf149f2ca
	v_add_u32_e32 v25, 0xffffff40, v21
	v_sub_u32_e32 v18, 0, v25
	v_max_i32_e32 v18, v25, v18
	v_cmp_lt_u32_e32 vcc, 0x80, v18
	s_nop 1
	v_cndmask_b32_e32 v24, v24, v23, vcc
	v_lshlrev_b32_e32 v25, 2, v21
	v_cmp_gt_u32_e32 vcc, 0x181, v21
	s_and_saveexec_b64 s[4:5], vcc
	ds_write_b32 v25, v24 offset:49152
	s_mov_b64 exec, s[4:5]
	s_mov_b32 s14, 0
	s_mov_b32 s30, 0x0
	s_mov_b32 s31, 0x18000
	s_waitcnt vmcnt(9) lgkmcnt(0)
	s_barrier
	s_cmpk_lt_u32 s15, 4
	s_cbranch_scc1 .Lswab_noskew
	s_barrier
